# ssd_out z loads and YMIX stores widened to dwordx4 via permlane16_swap (on top of gate_up K-loop drain removal)
# baseline (speedup 1.0000x reference)
.LBB0_577:
	v_lshl_or_b32 v2, s14, 4, v125
	v_lshl_add_u64 v[160:161], v[2:3], 0, s[92:93]
	v_mad_u64_u32 v[80:81], s[10:11], v160, s34, v[150:151]
	v_mad_i32_i24 v82, v2, s64, v172
	v_lshl_add_u32 v68, v2, 2, s12
	v_mad_i32_i24 v81, v161, s34, v81
	ds_read_b128 v[72:75], v82 offset:16384
	ds_read_b32 v181, v68 offset:8192
	ds_read_b128 v[100:103], v82 offset:16448
	ds_read_b128 v[88:91], v82 offset:16512
	v_bfe_u32 v196, v193, 4, 1
	v_mul_u32_u24_e32 v196, 24, v196
	v_mov_b32_e32 v197, 0
	v_lshl_add_u64 v[80:81], v[80:81], 0, v[196:197]
	global_load_dwordx4 v[208:211], v[80:81], off offset:1536
	global_load_dwordx4 v[212:215], v[80:81], off offset:1600
	s_waitcnt lgkmcnt(3)
	v_mfma_f32_16x16x32_bf16 v[68:71], v[4:7], v[72:75], 0
	ds_read_b128 v[104:107], v82 offset:16576
	s_add_i32 s10, s14, 1
	s_mul_i32 s10, s10, s14
	v_mfma_f32_16x16x32_bf16 v[76:79], v[36:39], v[72:75], 0
	s_lshr_b32 s62, s10, 1
	s_and_b32 s18, s14, -2
	v_mov_b32_e32 v96, 0
	s_waitcnt lgkmcnt(2)
	v_mfma_f32_16x16x32_bf16 v[68:71], v[8:11], v[100:103], v[68:71]
	s_mov_b32 s15, 0
	s_add_i32 s18, s18, 2
	v_lshl_add_u32 v182, s62, 9, v177
	v_mfma_f32_16x16x32_bf16 v[76:79], v[40:43], v[100:103], v[76:79]
	v_mov_b32_e32 v183, v180
	v_mov_b32_e32 v184, v127
	v_mov_b32_e32 v97, v96
	s_waitcnt lgkmcnt(1)
	v_mfma_f32_16x16x32_bf16 v[68:71], v[12:15], v[88:91], v[68:71]
	v_mov_b32_e32 v98, v96
	v_mov_b32_e32 v99, v96
	v_mov_b32_e32 v84, v96
	v_mfma_f32_16x16x32_bf16 v[76:79], v[44:47], v[88:91], v[76:79]
	v_mov_b32_e32 v85, v96
	v_mov_b32_e32 v86, v96
	v_mov_b32_e32 v87, v96
	s_waitcnt lgkmcnt(0)
	v_mfma_f32_16x16x32_bf16 v[92:95], v[16:19], v[104:107], v[68:71]
	v_mov_b32_e32 v80, v96
	v_mov_b32_e32 v81, v96
	v_mov_b32_e32 v82, v96
	v_mfma_f32_16x16x32_bf16 v[76:79], v[48:51], v[104:107], v[76:79]
	v_mov_b32_e32 v83, v96
	v_mov_b32_e32 v68, v96
	v_mov_b32_e32 v69, v96
	v_mov_b32_e32 v70, v96
	v_mov_b32_e32 v71, v96
	s_branch .LBB0_580

.LBB0_582:
	v_mfma_f32_16x16x32_bf16 v[108:111], v[20:23], v[72:75], 0
	v_mfma_f32_16x16x32_bf16 v[72:75], v[52:55], v[72:75], 0
	v_mfma_f32_16x16x32_bf16 v[108:111], v[24:27], v[100:103], v[108:111]
	v_mfma_f32_16x16x32_bf16 v[72:75], v[56:59], v[100:103], v[72:75]
	v_mfma_f32_16x16x32_bf16 v[100:103], v[28:31], v[88:91], v[108:111]
	v_mfma_f32_16x16x32_bf16 v[72:75], v[60:63], v[88:91], v[72:75]
	v_mfma_f32_16x16x32_bf16 v[88:91], v[32:35], v[104:107], v[100:103]
	s_nop 5
	v_exp_f32_e32 v100, v181
	v_lshl_add_u32 v101, v2, 1, s70
	s_waitcnt vmcnt(1)
	v_permlane16_swap_b32_e32 v208, v210
	v_permlane16_swap_b32_e32 v209, v211
	v_lshlrev_b32_e32 v102, 16, v208
	v_and_b32_e32 v103, 0xffff0000, v208
	v_mfma_f32_16x16x32_bf16 v[72:75], v[64:67], v[104:107], v[72:75]
	v_add_u32_e32 v108, v101, v1
	v_mul_f32_e32 v104, 0xbfb8aa3b, v102
	v_pk_fma_f32 v[92:93], v[100:101], v[92:93], v[96:97] op_sel_hi:[0,1,1]
	v_mul_f32_e32 v96, 0xbfb8aa3b, v103
	ds_read_u16 v105, v108
	ds_read_u16 v106, v108 offset:264
	v_exp_f32_e32 v104, v104
	v_exp_f32_e32 v96, v96
	v_pk_fma_f32 v[94:95], v[100:101], v[94:95], v[98:99] op_sel_hi:[0,1,1]
	v_pk_fma_f32 v[84:85], v[100:101], v[88:89], v[84:85] op_sel_hi:[0,1,1]
	v_add_f32_e32 v104, 1.0, v104
	v_add_f32_e32 v96, 1.0, v96
	v_rcp_f32_e32 v104, v104
	s_waitcnt lgkmcnt(0)
	v_lshlrev_b32_e32 v107, 16, v106
	v_lshlrev_b32_e32 v106, 16, v105
	v_rcp_f32_e32 v105, v96
	v_pk_fma_f32 v[92:93], v[148:149], v[106:107], v[92:93]
	v_pk_fma_f32 v[86:87], v[100:101], v[90:91], v[86:87] op_sel_hi:[0,1,1]
	v_pk_fma_f32 v[76:77], v[100:101], v[76:77], v[80:81] op_sel_hi:[0,1,1]
	v_pk_mul_f32 v[96:97], v[104:105], v[102:103]
	ds_read_u16 v105, v108 offset:528
	ds_read_u16 v106, v108 offset:792
	v_pk_mul_f32 v[102:103], v[96:97], v[92:93]
	v_lshlrev_b32_e32 v96, 16, v209
	v_and_b32_e32 v97, 0xffff0000, v209
	v_mul_f32_e32 v104, 0xbfb8aa3b, v96
	v_mul_f32_e32 v98, 0xbfb8aa3b, v97
	v_exp_f32_e32 v104, v104
	v_exp_f32_e32 v98, v98
	s_waitcnt lgkmcnt(0)
	v_lshlrev_b32_e32 v107, 16, v106
	v_lshlrev_b32_e32 v106, 16, v105
	v_add_f32_e32 v104, 1.0, v104
	v_add_f32_e32 v98, 1.0, v98
	v_rcp_f32_e32 v104, v104
	v_rcp_f32_e32 v105, v98
	v_pk_fma_f32 v[94:95], v[148:149], v[106:107], v[94:95]
	v_cvt_pk_bf16_f32 v208, v102, v103
	v_pk_mul_f32 v[92:93], v[102:103], v[102:103]
	v_pk_mul_f32 v[96:97], v[104:105], v[96:97]
	v_add_u32_e32 v106, v101, v131
	v_pk_mul_f32 v[94:95], v[96:97], v[94:95]
	v_pk_fma_f32 v[78:79], v[100:101], v[78:79], v[82:83] op_sel_hi:[0,1,1]
	v_pk_mul_f32 v[96:97], v[94:95], v[94:95]
	v_cvt_pk_bf16_f32 v209, v94, v95
	v_mad_u64_u32 v[94:95], s[10:11], v160, s37, v[152:153]
	v_mad_i32_i24 v95, v161, s37, v95
	s_waitcnt vmcnt(3)
	v_lshlrev_b32_e32 v98, 16, v210
	v_and_b32_e32 v99, 0xffff0000, v210
	v_mul_f32_e32 v102, 0xbfb8aa3b, v98
	v_mul_f32_e32 v88, 0xbfb8aa3b, v99
	ds_read_u16 v103, v106
	ds_read_u16 v104, v106 offset:264
	v_exp_f32_e32 v102, v102
	v_exp_f32_e32 v88, v88
	v_pk_fma_f32 v[68:69], v[100:101], v[72:73], v[68:69] op_sel_hi:[0,1,1]
	v_pk_fma_f32 v[70:71], v[100:101], v[74:75], v[70:71] op_sel_hi:[0,1,1]
	v_add_f32_e32 v102, 1.0, v102
	v_add_f32_e32 v88, 1.0, v88
	v_rcp_f32_e32 v102, v102
	s_waitcnt lgkmcnt(0)
	v_lshlrev_b32_e32 v105, 16, v104
	v_lshlrev_b32_e32 v104, 16, v103
	v_rcp_f32_e32 v103, v88
	v_pk_fma_f32 v[84:85], v[148:149], v[104:105], v[84:85]
	v_pk_mul_f32 v[88:89], v[102:103], v[98:99]
	v_lshlrev_b32_e32 v98, 16, v211
	v_and_b32_e32 v99, 0xffff0000, v211
	v_mul_f32_e32 v102, 0xbfb8aa3b, v98
	v_mul_f32_e32 v90, 0xbfb8aa3b, v99
	ds_read_u16 v103, v106 offset:528
	ds_read_u16 v104, v106 offset:792
	v_exp_f32_e32 v102, v102
	v_exp_f32_e32 v90, v90
	v_pk_mul_f32 v[88:89], v[88:89], v[84:85]
	v_add_f32_e32 v102, 1.0, v102
	v_add_f32_e32 v90, 1.0, v90
	v_rcp_f32_e32 v102, v102
	s_waitcnt lgkmcnt(0)
	v_lshlrev_b32_e32 v105, 16, v104
	v_lshlrev_b32_e32 v104, 16, v103
	v_rcp_f32_e32 v103, v90
	v_pk_fma_f32 v[86:87], v[148:149], v[104:105], v[86:87]
	v_pk_mul_f32 v[84:85], v[88:89], v[88:89]
	v_cvt_pk_bf16_f32 v210, v88, v89
	v_pk_mul_f32 v[90:91], v[102:103], v[98:99]
	v_add_u32_e32 v102, v101, v175
	v_pk_mul_f32 v[90:91], v[90:91], v[86:87]
	s_nop 0
	v_cvt_pk_bf16_f32 v211, v90, v91
	s_nop 1
	v_permlane16_swap_b32_e32 v208, v210
	v_permlane16_swap_b32_e32 v209, v211
	v_lshl_add_u64 v[94:95], v[94:95], 0, v[196:197]
	global_store_dwordx4 v[94:95], v[208:211], off
	s_waitcnt vmcnt(1)
	v_permlane16_swap_b32_e32 v212, v214
	v_permlane16_swap_b32_e32 v213, v215
	v_lshlrev_b32_e32 v88, 16, v212
	v_and_b32_e32 v89, 0xffff0000, v212
	v_pk_mul_f32 v[86:87], v[90:91], v[90:91]
	v_mul_f32_e32 v90, 0xbfb8aa3b, v88
	v_mul_f32_e32 v80, 0xbfb8aa3b, v89
	ds_read_u16 v91, v102
	ds_read_u16 v98, v102 offset:264
	v_exp_f32_e32 v90, v90
	v_exp_f32_e32 v80, v80
	v_add_f32_e32 v90, 1.0, v90
	v_add_f32_e32 v80, 1.0, v80
	v_rcp_f32_e32 v90, v90
	s_waitcnt lgkmcnt(0)
	v_lshlrev_b32_e32 v99, 16, v98
	v_lshlrev_b32_e32 v98, 16, v91
	v_rcp_f32_e32 v91, v80
	v_pk_fma_f32 v[76:77], v[148:149], v[98:99], v[76:77]
	v_pk_mul_f32 v[80:81], v[90:91], v[88:89]
	v_lshlrev_b32_e32 v88, 16, v213
	v_and_b32_e32 v89, 0xffff0000, v213
	v_mul_f32_e32 v90, 0xbfb8aa3b, v88
	v_mul_f32_e32 v82, 0xbfb8aa3b, v89
	ds_read_u16 v91, v102 offset:528
	ds_read_u16 v98, v102 offset:792
	v_exp_f32_e32 v90, v90
	v_exp_f32_e32 v82, v82
	v_pk_mul_f32 v[80:81], v[80:81], v[76:77]
	v_add_f32_e32 v90, 1.0, v90
	v_add_f32_e32 v82, 1.0, v82
	v_rcp_f32_e32 v90, v90
	s_waitcnt lgkmcnt(0)
	v_lshlrev_b32_e32 v99, 16, v98
	v_lshlrev_b32_e32 v98, 16, v91
	v_rcp_f32_e32 v91, v82
	v_pk_fma_f32 v[78:79], v[148:149], v[98:99], v[78:79]
	v_pk_mul_f32 v[76:77], v[80:81], v[80:81]
	v_cvt_pk_bf16_f32 v212, v80, v81
	v_pk_mul_f32 v[82:83], v[90:91], v[88:89]
	v_add_u32_e32 v90, v101, v176
	v_pk_mul_f32 v[82:83], v[82:83], v[78:79]
	s_nop 0
	v_cvt_pk_bf16_f32 v213, v82, v83
	s_waitcnt vmcnt(3)
	v_lshlrev_b32_e32 v80, 16, v214
	v_and_b32_e32 v81, 0xffff0000, v214
	v_pk_mul_f32 v[78:79], v[82:83], v[82:83]
	v_mul_f32_e32 v82, 0xbfb8aa3b, v80
	v_mul_f32_e32 v72, 0xbfb8aa3b, v81
	ds_read_u16 v83, v90
	ds_read_u16 v88, v90 offset:264
	v_exp_f32_e32 v82, v82
	v_exp_f32_e32 v72, v72
	v_add_f32_e32 v82, 1.0, v82
	v_add_f32_e32 v72, 1.0, v72
	v_rcp_f32_e32 v82, v82
	s_waitcnt lgkmcnt(0)
	v_lshlrev_b32_e32 v89, 16, v88
	v_lshlrev_b32_e32 v88, 16, v83
	v_rcp_f32_e32 v83, v72
	v_pk_fma_f32 v[68:69], v[148:149], v[88:89], v[68:69]
	v_pk_mul_f32 v[72:73], v[82:83], v[80:81]
	v_lshlrev_b32_e32 v80, 16, v215
	v_and_b32_e32 v81, 0xffff0000, v215
	v_mul_f32_e32 v82, 0xbfb8aa3b, v80
	v_mul_f32_e32 v74, 0xbfb8aa3b, v81
	ds_read_u16 v83, v90 offset:528
	ds_read_u16 v88, v90 offset:792
	v_exp_f32_e32 v82, v82
	v_exp_f32_e32 v74, v74
	v_pk_mul_f32 v[68:69], v[72:73], v[68:69]
	v_add_f32_e32 v82, 1.0, v82
	v_add_f32_e32 v74, 1.0, v74
	v_rcp_f32_e32 v82, v82
	s_waitcnt lgkmcnt(0)
	v_lshlrev_b32_e32 v89, 16, v88
	v_lshlrev_b32_e32 v88, 16, v83
	v_rcp_f32_e32 v83, v74
	v_pk_mul_f32 v[72:73], v[68:69], v[68:69]
	v_pk_fma_f32 v[70:71], v[148:149], v[88:89], v[70:71]
	v_cvt_pk_bf16_f32 v214, v68, v69
	v_pk_mul_f32 v[74:75], v[82:83], v[80:81]
	v_add_f32_e32 v80, v92, v93
	v_add_f32_e32 v80, v80, v96
	v_add_f32_e32 v80, v80, v97
	v_add_f32_e32 v80, v80, v84
	v_add_f32_e32 v80, v80, v85
	v_add_f32_e32 v80, v80, v86
	v_add_f32_e32 v80, v80, v87
	v_add_f32_e32 v76, v80, v76
	v_add_f32_e32 v76, v76, v77
	v_add_f32_e32 v76, v76, v78
	v_add_f32_e32 v76, v76, v79
	v_pk_mul_f32 v[70:71], v[74:75], v[70:71]
	v_add_f32_e32 v72, v76, v72
	v_pk_mul_f32 v[74:75], v[70:71], v[70:71]
	v_add_f32_e32 v72, v72, v73
	v_add_f32_e32 v72, v72, v74
	v_add_f32_e32 v72, v72, v75
	v_cvt_pk_bf16_f32 v215, v70, v71
	s_nop 1
	v_permlane16_swap_b32_e32 v212, v214
	v_permlane16_swap_b32_e32 v213, v215
	global_store_dwordx4 v[94:95], v[212:215], off offset:64
	ds_bpermute_b32 v68, v173, v72
	s_waitcnt lgkmcnt(0)
	v_add_f32_e32 v68, v72, v68
	ds_bpermute_b32 v69, v174, v68
	s_and_saveexec_b64 s[10:11], s[38:39]
	s_cbranch_execz .LBB0_571
	s_waitcnt lgkmcnt(0)
	v_add_f32_e32 v68, v68, v69
	v_lshl_add_u32 v2, v2, 5, s13
	ds_write_b32 v2, v68
	s_branch .LBB0_571
